# GEMM: no drain-all wait at the top of the bf16-store epilogue; first K-iteration peeled (C=0, no accumulator zeroing) with waits that leave the previous unit's stores outstanding
# speedup vs baseline: 1.0022x; 1.0020x over previous
.LBB0_584:
	s_add_u32 s8, s14, 0x6000000
	s_addc_u32 s9, s15, 0
	v_writelane_b32 v254, s8, 29
	v_lshl_add_u64 v[8:9], v[8:9], 0, s[16:17]
	s_waitcnt vmcnt(2)
	s_barrier
	v_writelane_b32 v254, s9, 30
	v_lshl_add_u64 v[4:5], v[4:5], 0, s[16:17]
	v_readlane_b32 s10, v254, 21
	s_and_b32 s7, 0xffff, s10
	s_mul_i32 s8, s7, 0x10800
	s_add_u32 s62, s44, s8
	s_addc_u32 s63, s45, 0
	s_mulk_i32 s7, 0x5800
	s_add_u32 s44, s46, s7
	s_addc_u32 s45, s47, 0
	s_add_u32 s8, s14, 0x80000
	s_addc_u32 s9, s15, 0
	s_lshl_b32 s7, s10, 4
	s_add_u32 s10, s68, s7
	s_addc_u32 s11, s69, 0
	v_writelane_b32 v254, s10, 31
	v_lshl_add_u64 v[2:3], v[2:3], 0, s[16:17]
	v_lshl_add_u64 v[0:1], v[0:1], 0, s[16:17]
	v_writelane_b32 v254, s11, 32
	s_add_u32 s10, s70, s7
	s_addc_u32 s11, s71, 0
	s_add_i32 s85, s24, 0x18000
	s_add_i32 s86, s85, s6
	s_mov_b32 m0, s86
	s_add_i32 s87, s86, 0x2000
	global_load_lds_dwordx4 v[8:9], off
	s_mov_b32 m0, s87
	s_add_i32 s88, s59, 0x8000
	global_load_lds_dwordx4 v[4:5], off
	v_lshl_add_u64 v[4:5], v[6:7], 0, s[16:17]
	s_mov_b32 m0, s88
	s_add_i32 s89, s59, 0xa000
	s_add_i32 s90, s24, 0x1c000
	global_load_lds_dwordx4 v[4:5], off
	v_lshl_add_u64 v[4:5], v[10:11], 0, s[16:17]
	s_mov_b32 m0, s89
	s_add_i32 s91, s90, s6
	global_load_lds_dwordx4 v[4:5], off
	s_mov_b32 m0, s91
	s_add_i32 s92, s91, 0x2000
	global_load_lds_dwordx4 v[2:3], off
	s_mov_b32 m0, s92
	v_and_b32_e32 v200, 15, v12
	global_load_lds_dwordx4 v[0:1], off
	v_bfe_u32 v1, v12, 4, 2
	v_lshlrev_b32_e32 v2, 3, v1
	v_lshlrev_b32_e32 v1, 4, v1
	v_lshlrev_b32_e32 v3, 2, v12
	s_and_b32 s6, s2, 3
	v_lshrrev_b32_e32 v0, 4, v12
	s_lshl_b32 s94, s3, 6
	v_lshl_or_b32 v1, v200, 6, v1
	s_lshl_b32 s3, s3, 13
	v_and_b32_e32 v3, 32, v3
	v_writelane_b32 v254, s10, 33
	v_bitop3_b32 v4, v1, s3, v3 bitop3:0xde
	s_lshl_b32 s3, s6, 12
	v_bitop3_b32 v0, s2, v0, 3 bitop3:0xa8
	v_writelane_b32 v254, s11, 34
	v_bitop3_b32 v201, v1, s3, v3 bitop3:0xde
	v_cmp_eq_u32_e64 s[2:3], 0, v0
	s_lshr_b32 s93, s12, 6
	v_add_u32_e32 v0, -14, v200
	v_writelane_b32 v254, s2, 35
	s_add_i32 s95, s93, -2
	s_cmpk_lt_u32 s20, 0x100
	v_writelane_b32 v254, s3, 36
	v_cmp_gt_u32_e64 s[2:3], -12, v0
	s_cselect_b64 s[20:21], -1, 0
	v_add_u32_e32 v0, -12, v200
	v_writelane_b32 v254, s2, 39
	v_cmp_gt_u32_e32 vcc, 2, v200
	s_lshr_b32 s60, s13, 5
	v_writelane_b32 v254, s3, 40
	s_lshr_b32 s2, s48, 3
	v_writelane_b32 v254, s2, 41
	v_cndmask_b32_e32 v202, v0, v200, vcc
	v_readlane_b32 s10, v254, 27
	v_cvt_f32_u32_e32 v0, s60
	s_ashr_i32 s97, s26, 31
	s_ashr_i32 s64, s27, 31
	s_and_b32 s34, s48, 7
	s_add_i32 s35, s2, 1
	v_readlane_b32 s11, v254, 28
	s_and_b64 s[2:3], s[10:11], exec
	s_cselect_b32 s61, 0xe00, s13
	s_add_u32 s2, s62, 0x5800
	s_addc_u32 s3, s63, 0
	v_rcp_iflag_f32_e32 v0, v0
	s_add_u32 s68, s62, 0xb000
	s_addc_u32 s69, s63, 0
	s_add_u32 s70, s62, 0x2c00
	s_addc_u32 s71, s63, 0
	v_mul_f32_e32 v0, 0x4f7ffffe, v0
	s_add_u32 s72, s62, 0x8400
	v_cvt_u32_f32_e32 v0, v0
	s_addc_u32 s73, s63, 0
	s_add_u32 s74, s62, 0xdc00
	v_writelane_b32 v254, s2, 21
	s_addc_u32 s75, s63, 0
	s_add_u32 s76, s44, 0x2c00
	v_writelane_b32 v254, s3, 22
	v_readfirstlane_b32 s7, v0
	v_add_u32_e32 v0, v15, v13
	v_writelane_b32 v254, s44, 43
	s_addc_u32 s77, s45, 0
	v_lshl_or_b32 v203, s6, 5, v2
	s_sub_i32 s6, 0, s60
	v_add_lshl_u32 v0, v0, v14, 1
	v_mov_b32_e32 v1, v113
	s_waitcnt vmcnt(6)
	v_writelane_b32 v254, s45, 44
	s_mul_i32 s6, s6, s7
	v_lshl_add_u64 v[168:169], s[66:67], 0, v[0:1]
	v_add_u32_e32 v0, v18, v16
	s_mul_hi_u32 s6, s7, s6
	v_add_lshl_u32 v0, v0, v17, 1
	v_writelane_b32 v254, s54, 45
	s_mov_b32 s96, 0
	v_cmp_lt_u32_e64 s[40:41], 1, v200
	s_mov_b32 s49, s67
	s_add_i32 s38, s7, s6
	v_lshl_add_u64 v[170:171], s[66:67], 0, v[0:1]
	v_add_u32_e32 v204, s24, v4
	v_writelane_b32 v254, s55, 46
	s_barrier
	s_mov_b32 s32, 0
	s_branch .LBB0_587

.LBB0_597:
	s_add_u32 s80, s4, 0x80
	s_addc_u32 s81, s5, 0
	s_add_u32 s4, s0, 0x100
	s_addc_u32 s5, s1, 0
	s_mov_b32 s0, 0
	v_add_u32_e32 v142, s31, v201
	v_add_u32_e32 v158, s56, v201
	ds_read_b128 v[130:133], v142
	ds_read_b128 v[134:137], v142 offset:1024
	ds_read_b128 v[138:141], v142 offset:2048
	ds_read_b128 v[142:145], v142 offset:3072
	ds_read_b128 v[146:149], v158
	ds_read_b128 v[150:153], v158 offset:1024
	ds_read_b128 v[154:157], v158 offset:2048
	ds_read_b128 v[158:161], v158 offset:3072
	s_add_i32 s6, s0, 2
	s_add_u32 s7, s80, 0x80
	s_addc_u32 s1, s81, 0
	s_cmp_eq_u32 s95, s0
	s_cselect_b32 s0, s46, s7
	s_cselect_b32 s1, s47, s1
	s_cselect_b32 vcc_hi, s79, s5
	s_cselect_b32 vcc_lo, s78, s4
	v_lshl_add_u64 v[210:211], s[80:81], 0, v[168:169]
	s_add_i32 m0, s59, 0xc000
	ds_read_b128 v[172:175], v204
	ds_read_b128 v[176:179], v204 offset:1024
	ds_read_b128 v[180:183], v204 offset:2048
	ds_read_b128 v[184:187], v204 offset:3072
	ds_read_b128 v[188:191], v204 offset:4096
	ds_read_b128 v[192:195], v204 offset:5120
	ds_read_b128 v[196:199], v204 offset:6144
	ds_read_b128 v[206:209], v204 offset:7168
	global_load_lds_dwordx4 v[210:211], off
	v_lshl_add_u64 v[210:211], s[80:81], 0, v[170:171]
	s_add_i32 m0, s59, 0xe000
	s_nop 0
	global_load_lds_dwordx4 v[210:211], off
	s_cmp_lg_u32 s32, 0
	s_cbranch_scc1 .Lpw24_0
	s_waitcnt vmcnt(8)
	s_branch .Lpwd_0
.Lpw24_0:
	s_waitcnt vmcnt(24)
.Lpwd_0:
	s_waitcnt lgkmcnt(0)
	s_barrier
	s_setprio 1
	s_waitcnt lgkmcnt(0)
	v_mfma_f32_16x16x32_bf16 v[68:71], v[130:133], v[172:175], 0
	v_mfma_f32_16x16x32_bf16 v[56:59], v[138:141], v[172:175], 0
	v_mfma_f32_16x16x32_bf16 v[52:55], v[130:133], v[180:183], 0
	v_mfma_f32_16x16x32_bf16 v[48:51], v[138:141], v[180:183], 0
	v_mfma_f32_16x16x32_bf16 v[44:47], v[130:133], v[188:191], 0
	v_mfma_f32_16x16x32_bf16 v[40:43], v[138:141], v[188:191], 0
	v_mfma_f32_16x16x32_bf16 v[36:39], v[130:133], v[196:199], 0
	v_mfma_f32_16x16x32_bf16 v[32:35], v[138:141], v[196:199], 0
	v_mfma_f32_16x16x32_bf16 v[68:71], v[134:137], v[176:179], v[68:71]
	v_mfma_f32_16x16x32_bf16 v[56:59], v[142:145], v[176:179], v[56:59]
	v_mfma_f32_16x16x32_bf16 v[52:55], v[134:137], v[184:187], v[52:55]
	v_mfma_f32_16x16x32_bf16 v[48:51], v[142:145], v[184:187], v[48:51]
	v_mfma_f32_16x16x32_bf16 v[44:47], v[134:137], v[192:195], v[44:47]
	v_mfma_f32_16x16x32_bf16 v[40:43], v[142:145], v[192:195], v[40:43]
	v_mfma_f32_16x16x32_bf16 v[36:39], v[134:137], v[206:209], v[36:39]
	v_mfma_f32_16x16x32_bf16 v[32:35], v[142:145], v[206:209], v[32:35]
	s_setprio 0
	s_setprio 1
	v_mfma_f32_16x16x32_bf16 v[126:129], v[146:149], v[172:175], 0
	v_mfma_f32_16x16x32_bf16 v[122:125], v[154:157], v[172:175], 0
	v_mfma_f32_16x16x32_bf16 v[118:121], v[146:149], v[180:183], 0
	v_mfma_f32_16x16x32_bf16 v[114:117], v[154:157], v[180:183], 0
	v_mfma_f32_16x16x32_bf16 v[108:111], v[146:149], v[188:191], 0
	v_mfma_f32_16x16x32_bf16 v[104:107], v[154:157], v[188:191], 0
	v_mfma_f32_16x16x32_bf16 v[100:103], v[146:149], v[196:199], 0
	v_mfma_f32_16x16x32_bf16 v[96:99], v[154:157], v[196:199], 0
	v_mfma_f32_16x16x32_bf16 v[126:129], v[150:153], v[176:179], v[126:129]
	v_mfma_f32_16x16x32_bf16 v[122:125], v[158:161], v[176:179], v[122:125]
	v_mfma_f32_16x16x32_bf16 v[118:121], v[150:153], v[184:187], v[118:121]
	v_mfma_f32_16x16x32_bf16 v[114:117], v[158:161], v[184:187], v[114:117]
	v_mfma_f32_16x16x32_bf16 v[108:111], v[150:153], v[192:195], v[108:111]
	v_mfma_f32_16x16x32_bf16 v[104:107], v[158:161], v[192:195], v[104:107]
	v_mfma_f32_16x16x32_bf16 v[100:103], v[150:153], v[206:209], v[100:103]
	v_mfma_f32_16x16x32_bf16 v[96:99], v[158:161], v[206:209], v[96:99]
	s_setprio 0
	s_barrier
	s_mov_b32 m0, s36
	v_lshl_add_u64 v[210:211], vcc, 0, v[112:113]
	v_lshl_add_u64 v[212:213], vcc, 0, v[166:167]
	s_add_u32 vcc_lo, vcc_lo, s66
	ds_read_b128 v[172:175], v204 offset:16384
	ds_read_b128 v[176:179], v204 offset:17408
	ds_read_b128 v[180:183], v204 offset:18432
	ds_read_b128 v[184:187], v204 offset:19456
	ds_read_b128 v[188:191], v204 offset:20480
	ds_read_b128 v[192:195], v204 offset:21504
	ds_read_b128 v[196:199], v204 offset:22528
	ds_read_b128 v[206:209], v204 offset:23552
	global_load_lds_dwordx4 v[210:211], off
	s_mov_b32 m0, s37
	s_addc_u32 vcc_hi, vcc_hi, 0
	global_load_lds_dwordx4 v[212:213], off
	v_lshl_add_u64 v[214:215], vcc, 0, v[112:113]
	s_mov_b32 m0, s57
	v_lshl_add_u64 v[216:217], vcc, 0, v[166:167]
	global_load_lds_dwordx4 v[214:215], off
	s_mov_b32 m0, s58
	v_lshl_add_u64 v[218:219], s[0:1], 0, v[162:163]
	global_load_lds_dwordx4 v[216:217], off
	s_mov_b32 m0, s59
	v_lshl_add_u64 v[220:221], s[0:1], 0, v[164:165]
	global_load_lds_dwordx4 v[218:219], off
	s_mov_b32 m0, s82
	s_nop 0
	global_load_lds_dwordx4 v[220:221], off
	s_cmp_lg_u32 s32, 0
	s_cbranch_scc1 .Lpw24_1
	s_waitcnt vmcnt(8)
	s_branch .Lpwd_1

.Lpwd_1:
	s_waitcnt lgkmcnt(0)
	s_barrier
	s_setprio 1
	s_waitcnt lgkmcnt(0)
	v_mfma_f32_16x16x32_bf16 v[28:31], v[130:133], v[172:175], 0
	v_mfma_f32_16x16x32_bf16 v[24:27], v[138:141], v[172:175], 0
	v_mfma_f32_16x16x32_bf16 v[20:23], v[130:133], v[180:183], 0
	v_mfma_f32_16x16x32_bf16 v[16:19], v[138:141], v[180:183], 0
	v_mfma_f32_16x16x32_bf16 v[12:15], v[130:133], v[188:191], 0
	v_mfma_f32_16x16x32_bf16 v[8:11], v[138:141], v[188:191], 0
	v_mfma_f32_16x16x32_bf16 v[4:7], v[130:133], v[196:199], 0
	v_mfma_f32_16x16x32_bf16 v[0:3], v[138:141], v[196:199], 0
	v_mfma_f32_16x16x32_bf16 v[28:31], v[134:137], v[176:179], v[28:31]
	v_mfma_f32_16x16x32_bf16 v[24:27], v[142:145], v[176:179], v[24:27]
	v_mfma_f32_16x16x32_bf16 v[20:23], v[134:137], v[184:187], v[20:23]
	v_mfma_f32_16x16x32_bf16 v[16:19], v[142:145], v[184:187], v[16:19]
	v_mfma_f32_16x16x32_bf16 v[12:15], v[134:137], v[192:195], v[12:15]
	v_mfma_f32_16x16x32_bf16 v[8:11], v[142:145], v[192:195], v[8:11]
	v_mfma_f32_16x16x32_bf16 v[4:7], v[134:137], v[206:209], v[4:7]
	v_mfma_f32_16x16x32_bf16 v[0:3], v[142:145], v[206:209], v[0:3]
	s_setprio 0
	s_setprio 1
	v_mfma_f32_16x16x32_bf16 v[92:95], v[146:149], v[172:175], 0
	v_mfma_f32_16x16x32_bf16 v[88:91], v[154:157], v[172:175], 0
	v_mfma_f32_16x16x32_bf16 v[84:87], v[146:149], v[180:183], 0
	v_mfma_f32_16x16x32_bf16 v[80:83], v[154:157], v[180:183], 0
	v_mfma_f32_16x16x32_bf16 v[76:79], v[146:149], v[188:191], 0
	v_mfma_f32_16x16x32_bf16 v[72:75], v[154:157], v[188:191], 0
	v_mfma_f32_16x16x32_bf16 v[64:67], v[146:149], v[196:199], 0
	v_mfma_f32_16x16x32_bf16 v[60:63], v[154:157], v[196:199], 0
	v_mfma_f32_16x16x32_bf16 v[92:95], v[150:153], v[176:179], v[92:95]
	v_mfma_f32_16x16x32_bf16 v[88:91], v[158:161], v[176:179], v[88:91]
	v_mfma_f32_16x16x32_bf16 v[84:87], v[150:153], v[184:187], v[84:87]
	v_mfma_f32_16x16x32_bf16 v[80:83], v[158:161], v[184:187], v[80:83]
	v_mfma_f32_16x16x32_bf16 v[76:79], v[150:153], v[192:195], v[76:79]
	v_mfma_f32_16x16x32_bf16 v[72:75], v[158:161], v[192:195], v[72:75]
	v_mfma_f32_16x16x32_bf16 v[64:67], v[150:153], v[206:209], v[64:67]
	v_mfma_f32_16x16x32_bf16 v[60:63], v[158:161], v[206:209], v[60:63]
	s_setprio 0
	s_barrier
	v_add_u32_e32 v142, s85, v201
	v_add_u32_e32 v158, s90, v201
	ds_read_b128 v[130:133], v142
	ds_read_b128 v[134:137], v142 offset:1024
	ds_read_b128 v[138:141], v142 offset:2048
	ds_read_b128 v[142:145], v142 offset:3072
	ds_read_b128 v[146:149], v158
	ds_read_b128 v[150:153], v158 offset:1024
	ds_read_b128 v[154:157], v158 offset:2048
	ds_read_b128 v[158:161], v158 offset:3072
	s_add_u32 s0, s0, s66
	s_addc_u32 s1, s1, 0
	s_mov_b32 m0, s83
	v_lshl_add_u64 v[222:223], s[0:1], 0, v[162:163]
	ds_read_b128 v[172:175], v204 offset:32768
	ds_read_b128 v[176:179], v204 offset:33792
	ds_read_b128 v[180:183], v204 offset:34816
	ds_read_b128 v[184:187], v204 offset:35840
	ds_read_b128 v[188:191], v204 offset:36864
	ds_read_b128 v[192:195], v204 offset:37888
	ds_read_b128 v[196:199], v204 offset:38912
	ds_read_b128 v[206:209], v204 offset:39936
	global_load_lds_dwordx4 v[222:223], off
	v_lshl_add_u64 v[222:223], s[0:1], 0, v[164:165]
	s_mov_b32 m0, s84
	s_nop 0
	global_load_lds_dwordx4 v[222:223], off
	s_waitcnt vmcnt(8)
	s_waitcnt lgkmcnt(0)
	s_barrier
	s_setprio 1
	s_waitcnt lgkmcnt(0)
	v_mfma_f32_16x16x32_bf16 v[68:71], v[130:133], v[172:175], v[68:71]
	v_mfma_f32_16x16x32_bf16 v[56:59], v[138:141], v[172:175], v[56:59]
	v_mfma_f32_16x16x32_bf16 v[52:55], v[130:133], v[180:183], v[52:55]
	v_mfma_f32_16x16x32_bf16 v[48:51], v[138:141], v[180:183], v[48:51]
	v_mfma_f32_16x16x32_bf16 v[44:47], v[130:133], v[188:191], v[44:47]
	v_mfma_f32_16x16x32_bf16 v[40:43], v[138:141], v[188:191], v[40:43]
	v_mfma_f32_16x16x32_bf16 v[36:39], v[130:133], v[196:199], v[36:39]
	v_mfma_f32_16x16x32_bf16 v[32:35], v[138:141], v[196:199], v[32:35]
	v_mfma_f32_16x16x32_bf16 v[68:71], v[134:137], v[176:179], v[68:71]
	v_mfma_f32_16x16x32_bf16 v[56:59], v[142:145], v[176:179], v[56:59]
	v_mfma_f32_16x16x32_bf16 v[52:55], v[134:137], v[184:187], v[52:55]
	v_mfma_f32_16x16x32_bf16 v[48:51], v[142:145], v[184:187], v[48:51]
	v_mfma_f32_16x16x32_bf16 v[44:47], v[134:137], v[192:195], v[44:47]
	v_mfma_f32_16x16x32_bf16 v[40:43], v[142:145], v[192:195], v[40:43]
	v_mfma_f32_16x16x32_bf16 v[36:39], v[134:137], v[206:209], v[36:39]
	v_mfma_f32_16x16x32_bf16 v[32:35], v[142:145], v[206:209], v[32:35]
	s_setprio 0
	s_setprio 1
	v_mfma_f32_16x16x32_bf16 v[126:129], v[146:149], v[172:175], v[126:129]
	v_mfma_f32_16x16x32_bf16 v[122:125], v[154:157], v[172:175], v[122:125]
	v_mfma_f32_16x16x32_bf16 v[118:121], v[146:149], v[180:183], v[118:121]
	v_mfma_f32_16x16x32_bf16 v[114:117], v[154:157], v[180:183], v[114:117]
	v_mfma_f32_16x16x32_bf16 v[108:111], v[146:149], v[188:191], v[108:111]
	v_mfma_f32_16x16x32_bf16 v[104:107], v[154:157], v[188:191], v[104:107]
	v_mfma_f32_16x16x32_bf16 v[100:103], v[146:149], v[196:199], v[100:103]
	v_mfma_f32_16x16x32_bf16 v[96:99], v[154:157], v[196:199], v[96:99]
	v_mfma_f32_16x16x32_bf16 v[126:129], v[150:153], v[176:179], v[126:129]
	v_mfma_f32_16x16x32_bf16 v[122:125], v[158:161], v[176:179], v[122:125]
	v_mfma_f32_16x16x32_bf16 v[118:121], v[150:153], v[184:187], v[118:121]
	v_mfma_f32_16x16x32_bf16 v[114:117], v[158:161], v[184:187], v[114:117]
	v_mfma_f32_16x16x32_bf16 v[108:111], v[150:153], v[192:195], v[108:111]
	v_mfma_f32_16x16x32_bf16 v[104:107], v[158:161], v[192:195], v[104:107]
	v_mfma_f32_16x16x32_bf16 v[100:103], v[150:153], v[206:209], v[100:103]
	v_mfma_f32_16x16x32_bf16 v[96:99], v[158:161], v[206:209], v[96:99]
	s_setprio 0
	s_barrier
	s_mov_b32 m0, s86
	v_lshl_add_u64 v[210:211], v[210:211], 0, s[16:17]
	ds_read_b128 v[172:175], v204 offset:49152
	ds_read_b128 v[176:179], v204 offset:50176
	ds_read_b128 v[180:183], v204 offset:51200
	ds_read_b128 v[184:187], v204 offset:52224
	ds_read_b128 v[188:191], v204 offset:53248
	ds_read_b128 v[192:195], v204 offset:54272
	ds_read_b128 v[196:199], v204 offset:55296
	ds_read_b128 v[206:209], v204 offset:56320
	global_load_lds_dwordx4 v[210:211], off
	v_lshl_add_u64 v[210:211], v[212:213], 0, s[16:17]
	s_mov_b32 m0, s87
	s_nop 0
	global_load_lds_dwordx4 v[210:211], off
	v_lshl_add_u64 v[210:211], v[214:215], 0, s[16:17]
	s_mov_b32 m0, s91
	s_nop 0
	global_load_lds_dwordx4 v[210:211], off
	v_lshl_add_u64 v[210:211], v[216:217], 0, s[16:17]
	s_mov_b32 m0, s92
	s_nop 0
	global_load_lds_dwordx4 v[210:211], off
	v_lshl_add_u64 v[210:211], v[218:219], 0, s[16:17]
	s_mov_b32 m0, s88
	s_nop 0
	global_load_lds_dwordx4 v[210:211], off
	v_lshl_add_u64 v[210:211], v[220:221], 0, s[16:17]
	s_mov_b32 m0, s89
	s_nop 0
	global_load_lds_dwordx4 v[210:211], off
	s_waitcnt vmcnt(8)
	s_waitcnt lgkmcnt(0)
	s_barrier
	s_setprio 1
	s_waitcnt lgkmcnt(0)
	v_mfma_f32_16x16x32_bf16 v[28:31], v[130:133], v[172:175], v[28:31]
	v_mfma_f32_16x16x32_bf16 v[24:27], v[138:141], v[172:175], v[24:27]
	v_mfma_f32_16x16x32_bf16 v[20:23], v[130:133], v[180:183], v[20:23]
	v_mfma_f32_16x16x32_bf16 v[16:19], v[138:141], v[180:183], v[16:19]
	v_mfma_f32_16x16x32_bf16 v[12:15], v[130:133], v[188:191], v[12:15]
	v_mfma_f32_16x16x32_bf16 v[8:11], v[138:141], v[188:191], v[8:11]
	v_mfma_f32_16x16x32_bf16 v[4:7], v[130:133], v[196:199], v[4:7]
	v_mfma_f32_16x16x32_bf16 v[0:3], v[138:141], v[196:199], v[0:3]
	v_mfma_f32_16x16x32_bf16 v[28:31], v[134:137], v[176:179], v[28:31]
	v_mfma_f32_16x16x32_bf16 v[24:27], v[142:145], v[176:179], v[24:27]
	v_mfma_f32_16x16x32_bf16 v[20:23], v[134:137], v[184:187], v[20:23]
	v_mfma_f32_16x16x32_bf16 v[16:19], v[142:145], v[184:187], v[16:19]
	v_mfma_f32_16x16x32_bf16 v[12:15], v[134:137], v[192:195], v[12:15]
	v_mfma_f32_16x16x32_bf16 v[8:11], v[142:145], v[192:195], v[8:11]
	v_mfma_f32_16x16x32_bf16 v[4:7], v[134:137], v[206:209], v[4:7]
	v_mfma_f32_16x16x32_bf16 v[0:3], v[142:145], v[206:209], v[0:3]
	s_setprio 0
	s_setprio 1
	v_mfma_f32_16x16x32_bf16 v[92:95], v[146:149], v[172:175], v[92:95]
	v_mfma_f32_16x16x32_bf16 v[88:91], v[154:157], v[172:175], v[88:91]
	v_mfma_f32_16x16x32_bf16 v[84:87], v[146:149], v[180:183], v[84:87]
	v_mfma_f32_16x16x32_bf16 v[80:83], v[154:157], v[180:183], v[80:83]
	v_mfma_f32_16x16x32_bf16 v[76:79], v[146:149], v[188:191], v[76:79]
	v_mfma_f32_16x16x32_bf16 v[72:75], v[154:157], v[188:191], v[72:75]
	v_mfma_f32_16x16x32_bf16 v[64:67], v[146:149], v[196:199], v[64:67]
	v_mfma_f32_16x16x32_bf16 v[60:63], v[154:157], v[196:199], v[60:63]
	v_mfma_f32_16x16x32_bf16 v[92:95], v[150:153], v[176:179], v[92:95]
	v_mfma_f32_16x16x32_bf16 v[88:91], v[158:161], v[176:179], v[88:91]
	v_mfma_f32_16x16x32_bf16 v[84:87], v[150:153], v[184:187], v[84:87]
	v_mfma_f32_16x16x32_bf16 v[80:83], v[158:161], v[184:187], v[80:83]
	v_mfma_f32_16x16x32_bf16 v[76:79], v[150:153], v[192:195], v[76:79]
	v_mfma_f32_16x16x32_bf16 v[72:75], v[158:161], v[192:195], v[72:75]
	v_mfma_f32_16x16x32_bf16 v[64:67], v[150:153], v[206:209], v[64:67]
	v_mfma_f32_16x16x32_bf16 v[60:63], v[158:161], v[206:209], v[60:63]
	s_setprio 0
	s_barrier
	s_add_u32 s80, s80, 0x100
	s_addc_u32 s81, s81, 0
	s_add_u32 s4, s4, 0x100
	s_addc_u32 s5, s5, 0
	s_cmp_ge_u32 s6, s93
	s_mov_b32 s0, s6
	s_cbranch_scc1 .Lgemm_k_done

.Lgemm_k_done:
	s_and_b64 vcc, exec, s[20:21]
	s_cbranch_vccz .LBB0_601
	s_barrier
.LBB0_601:
	s_mov_b32 s32, 0
	s_lshl_b32 s4, s42, 8
	s_add_i32 s4, s4, s94
	v_or_b32_e32 v172, s4, v200
	v_lshl_or_b32 v174, s39, 8, v203
	s_cmp_lt_i32 s23, 2
	s_mov_b64 s[0:1], -1
	s_cbranch_scc1 .LBB0_641
	s_cmp_gt_i32 s23, 2
	s_cbranch_scc0 .LBB0_638
	v_lshl_or_b32 v176, s39, 7, v203
	v_ashrrev_i32_e32 v177, 31, v176
	v_readlane_b32 s0, v254, 21
	v_lshlrev_b64 v[142:143], 2, v[176:177]
	v_readlane_b32 s1, v254, 22
	v_lshl_add_u64 v[180:181], s[62:63], 0, v[142:143]
	global_load_dwordx4 v[146:149], v[180:181], off
	v_lshl_add_u64 v[130:131], s[0:1], 0, v[142:143]
	v_readlane_b32 s0, v254, 43
	v_readlane_b32 s1, v254, 44
	v_lshl_add_u64 v[132:133], s[68:69], 0, v[142:143]
	global_load_dwordx4 v[150:153], v[130:131], off
	global_load_dwordx4 v[154:157], v[132:133], off
	v_lshl_add_u64 v[182:183], s[0:1], 0, v[142:143]
	v_lshl_add_u64 v[130:131], s[70:71], 0, v[142:143]
	v_lshl_add_u64 v[134:135], s[72:73], 0, v[142:143]
	v_lshl_add_u64 v[138:139], s[74:75], 0, v[142:143]
	v_lshl_add_u64 v[142:143], s[76:77], 0, v[142:143]
	global_load_dwordx4 v[158:161], v[182:183], off
	s_nop 0
	global_load_dwordx4 v[130:133], v[130:131], off
	s_nop 0
	global_load_dwordx4 v[134:137], v[134:135], off
	v_lshl_add_u64 v[178:179], v[176:177], 1, s[52:53]
	global_load_dwordx4 v[138:141], v[138:139], off
	v_mov_b32_dpp v198, v68 row_shr:2 row_mask:0xf bank_mask:0xf bound_ctrl:1
	global_load_dwordx4 v[142:145], v[142:143], off
	v_mov_b32_dpp v196, v68 row_shr:1 row_mask:0xf bank_mask:0xf bound_ctrl:1
	v_mov_b32_dpp v194, v126 row_shr:2 row_mask:0xf bank_mask:0xf bound_ctrl:1
	v_mov_b32_dpp v192, v126 row_shr:1 row_mask:0xf bank_mask:0xf bound_ctrl:1
	v_mov_b32_dpp v199, v69 row_shr:2 row_mask:0xf bank_mask:0xf bound_ctrl:1
	v_mov_b32_dpp v197, v69 row_shr:1 row_mask:0xf bank_mask:0xf bound_ctrl:1
	v_mov_b32_dpp v195, v127 row_shr:2 row_mask:0xf bank_mask:0xf bound_ctrl:1
	v_mov_b32_dpp v193, v127 row_shr:1 row_mask:0xf bank_mask:0xf bound_ctrl:1
	v_mov_b32_dpp v190, v70 row_shr:2 row_mask:0xf bank_mask:0xf bound_ctrl:1
	v_mov_b32_dpp v188, v70 row_shr:1 row_mask:0xf bank_mask:0xf bound_ctrl:1
	v_mov_b32_dpp v186, v128 row_shr:2 row_mask:0xf bank_mask:0xf bound_ctrl:1
	v_mov_b32_dpp v184, v128 row_shr:1 row_mask:0xf bank_mask:0xf bound_ctrl:1
	v_mov_b32_dpp v191, v71 row_shr:2 row_mask:0xf bank_mask:0xf bound_ctrl:1
	v_mov_b32_dpp v189, v71 row_shr:1 row_mask:0xf bank_mask:0xf bound_ctrl:1
	v_mov_b32_dpp v187, v129 row_shr:2 row_mask:0xf bank_mask:0xf bound_ctrl:1
	v_mov_b32_dpp v185, v129 row_shr:1 row_mask:0xf bank_mask:0xf bound_ctrl:1
	s_and_saveexec_b64 s[0:1], s[40:41]
	s_movk_i32 s5, 0x1600
	s_cbranch_execz .LBB0_605
	s_waitcnt vmcnt(0)
	v_pk_fma_f32 v[198:199], v[146:147], v[198:199], v[158:159]
	v_pk_fma_f32 v[190:191], v[148:149], v[190:191], v[160:161]
	v_pk_fma_f32 v[196:197], v[150:151], v[196:197], v[198:199]
	v_pk_fma_f32 v[188:189], v[152:153], v[188:189], v[190:191]
	v_pk_fma_f32 v[196:197], v[68:69], v[154:155], v[196:197]
	v_pk_fma_f32 v[188:189], v[70:71], v[156:157], v[188:189]
	v_mul_f32_e32 v173, 0x3dd2d3e8, v196
	v_fmaak_f32 v173, v196, v173, 0x40135761
	v_mul_f32_e32 v175, 0x3dd2d3e8, v197
	v_mul_f32_e32 v173, v196, v173
	v_fmaak_f32 v175, v197, v175, 0x40135761
	v_exp_f32_e32 v173, v173
	v_mul_f32_e32 v175, v197, v175
	v_exp_f32_e32 v175, v175
	v_pk_fma_f32 v[194:195], v[130:131], v[194:195], v[142:143]
	v_add_f32_e32 v173, 1.0, v173
	v_rcp_f32_e32 v198, v173
	v_add_f32_e32 v173, 1.0, v175
	v_rcp_f32_e32 v199, v173
	v_mul_f32_e32 v173, 0x3dd2d3e8, v188
	v_fmaak_f32 v173, v188, v173, 0x40135761
	v_mul_f32_e32 v175, 0x3dd2d3e8, v189
	v_mul_f32_e32 v173, v188, v173
	v_fmaak_f32 v175, v189, v175, 0x40135761
	v_exp_f32_e32 v173, v173
	v_mul_f32_e32 v175, v189, v175
	v_exp_f32_e32 v175, v175
	v_pk_fma_f32 v[192:193], v[134:135], v[192:193], v[194:195]
	v_pk_fma_f32 v[194:195], v[196:197], v[198:199], v[196:197] neg_lo:[1,0,0] neg_hi:[1,0,0]
	v_pk_fma_f32 v[192:193], v[126:127], v[138:139], v[192:193]
	v_add_f32_e32 v173, 1.0, v173
	v_pk_mul_f32 v[190:191], v[192:193], v[194:195]
	v_rcp_f32_e32 v192, v173
	v_add_f32_e32 v173, 1.0, v175
	v_rcp_f32_e32 v193, v173
	v_pk_fma_f32 v[186:187], v[132:133], v[186:187], v[144:145]
	s_nop 0
	v_pk_fma_f32 v[184:185], v[136:137], v[184:185], v[186:187]
	v_pk_fma_f32 v[186:187], v[188:189], v[192:193], v[188:189] neg_lo:[1,0,0] neg_hi:[1,0,0]
	v_pk_fma_f32 v[184:185], v[128:129], v[140:141], v[184:185]
	s_nop 0
	v_pk_mul_f32 v[184:185], v[184:185], v[186:187]
	v_cvt_pk_bf16_f32 v186, v190, v191
	v_cvt_pk_bf16_f32 v187, v184, v185
	v_mad_i64_i32 v[184:185], s[6:7], v172, s5, v[178:179]
	global_store_dwordx2 v[184:185], v[186:187], off

.LBB0_637:
	s_mov_b32 s32, 1
	s_or_b64 exec, exec, s[0:1]
	s_mov_b64 s[0:1], 0

.LBB0_645:
	s_and_b32 s0, s39, -2
	s_cmp_eq_u32 s0, 8
	s_cselect_b64 vcc, -1, 0
	v_mov_b32_e32 v130, 0x3db504f3
	s_cmp_gt_i32 s39, 1
	v_cndmask_b32_e32 v130, 1.0, v130, vcc
	s_cselect_b64 vcc, -1, 0
	v_mov_b32_e32 v131, 0x3e38aa3b
	v_cndmask_b32_e32 v130, v131, v130, vcc
	v_ashrrev_i32_e32 v131, 31, v172
	v_mul_lo_u32 v131, s61, v131
	v_mad_u64_u32 v[132:133], s[0:1], s61, v172, 0
	v_ashrrev_i32_e32 v175, 31, v174
	v_add_u32_e32 v133, v133, v131
	v_cndmask_b32_e64 v130, 1.0, v130, s[10:11]
	v_lshl_add_u64 v[134:135], v[132:133], 1, s[52:53]
	v_lshlrev_b64 v[132:133], 1, v[174:175]
	v_lshl_add_u64 v[138:139], v[134:135], 0, v[132:133]
	v_pk_mul_f32 v[136:137], v[130:131], v[70:71] op_sel_hi:[0,1]
	v_pk_mul_f32 v[134:135], v[130:131], v[68:69] op_sel_hi:[0,1]
	v_pk_mul_f32 v[140:141], v[130:131], v[58:59] op_sel_hi:[0,1]
	v_pk_mul_f32 v[142:143], v[130:131], v[56:57] op_sel_hi:[0,1]
	v_cvt_pk_bf16_f32 v134, v134, v135
	v_cvt_pk_bf16_f32 v135, v136, v137
	v_cvt_pk_bf16_f32 v136, v142, v143
	v_cvt_pk_bf16_f32 v137, v140, v141
	global_store_dwordx4 v[138:139], v[134:137], off
	v_pk_mul_f32 v[128:129], v[130:131], v[128:129] op_sel_hi:[0,1]
	v_pk_mul_f32 v[126:127], v[130:131], v[126:127] op_sel_hi:[0,1]
	v_pk_mul_f32 v[134:135], v[130:131], v[124:125] op_sel_hi:[0,1]
	v_pk_mul_f32 v[124:125], v[130:131], v[122:123] op_sel_hi:[0,1]
	v_cvt_pk_bf16_f32 v122, v126, v127
	v_cvt_pk_bf16_f32 v123, v128, v129
	v_cvt_pk_bf16_f32 v124, v124, v125
	v_cvt_pk_bf16_f32 v125, v134, v135
	global_store_dwordx4 v[138:139], v[122:125], off offset:256
	v_pk_mul_f32 v[128:129], v[130:131], v[50:51] op_sel_hi:[0,1]
	v_pk_mul_f32 v[134:135], v[130:131], v[48:49] op_sel_hi:[0,1]
	v_or_b32_e32 v122, 16, v172
	v_mad_u64_u32 v[122:123], s[0:1], s61, v122, 0
	v_add_u32_e32 v123, v123, v131
	v_lshl_add_u64 v[122:123], v[122:123], 1, s[52:53]
	v_lshl_add_u64 v[126:127], v[122:123], 0, v[132:133]
	v_pk_mul_f32 v[124:125], v[130:131], v[54:55] op_sel_hi:[0,1]
	v_pk_mul_f32 v[122:123], v[130:131], v[52:53] op_sel_hi:[0,1]
	v_cvt_pk_bf16_f32 v122, v122, v123
	v_cvt_pk_bf16_f32 v123, v124, v125
	v_cvt_pk_bf16_f32 v124, v134, v135
	v_cvt_pk_bf16_f32 v125, v128, v129
	global_store_dwordx4 v[126:127], v[122:125], off
	v_pk_mul_f32 v[120:121], v[130:131], v[120:121] op_sel_hi:[0,1]
	v_pk_mul_f32 v[118:119], v[130:131], v[118:119] op_sel_hi:[0,1]
	v_pk_mul_f32 v[122:123], v[130:131], v[116:117] op_sel_hi:[0,1]
	v_pk_mul_f32 v[116:117], v[130:131], v[114:115] op_sel_hi:[0,1]
	v_cvt_pk_bf16_f32 v114, v118, v119
	v_cvt_pk_bf16_f32 v115, v120, v121
	v_cvt_pk_bf16_f32 v116, v116, v117
	v_cvt_pk_bf16_f32 v117, v122, v123
	global_store_dwordx4 v[126:127], v[114:117], off offset:256
	v_pk_mul_f32 v[120:121], v[130:131], v[42:43] op_sel_hi:[0,1]
	v_pk_mul_f32 v[122:123], v[130:131], v[40:41] op_sel_hi:[0,1]
	v_or_b32_e32 v114, 32, v172
	v_mad_u64_u32 v[114:115], s[0:1], s61, v114, 0
	v_add_u32_e32 v115, v115, v131
	v_lshl_add_u64 v[114:115], v[114:115], 1, s[52:53]
	v_lshl_add_u64 v[118:119], v[114:115], 0, v[132:133]
	v_pk_mul_f32 v[116:117], v[130:131], v[46:47] op_sel_hi:[0,1]
	v_pk_mul_f32 v[114:115], v[130:131], v[44:45] op_sel_hi:[0,1]
	v_cvt_pk_bf16_f32 v114, v114, v115
	v_cvt_pk_bf16_f32 v115, v116, v117
	v_cvt_pk_bf16_f32 v116, v122, v123
	v_cvt_pk_bf16_f32 v117, v120, v121
	global_store_dwordx4 v[118:119], v[114:117], off
	v_pk_mul_f32 v[110:111], v[130:131], v[110:111] op_sel_hi:[0,1]
	v_pk_mul_f32 v[108:109], v[130:131], v[108:109] op_sel_hi:[0,1]
	v_pk_mul_f32 v[114:115], v[130:131], v[106:107] op_sel_hi:[0,1]
	v_pk_mul_f32 v[106:107], v[130:131], v[104:105] op_sel_hi:[0,1]
	v_cvt_pk_bf16_f32 v104, v108, v109
	v_cvt_pk_bf16_f32 v105, v110, v111
	v_cvt_pk_bf16_f32 v106, v106, v107
	v_cvt_pk_bf16_f32 v107, v114, v115
	global_store_dwordx4 v[118:119], v[104:107], off offset:256
	v_pk_mul_f32 v[110:111], v[130:131], v[34:35] op_sel_hi:[0,1]
	v_pk_mul_f32 v[114:115], v[130:131], v[32:33] op_sel_hi:[0,1]
	v_or_b32_e32 v104, 48, v172
	v_mad_u64_u32 v[104:105], s[0:1], s61, v104, 0
	v_add_u32_e32 v105, v105, v131
	v_lshl_add_u64 v[104:105], v[104:105], 1, s[52:53]
	v_lshl_add_u64 v[108:109], v[104:105], 0, v[132:133]
	v_pk_mul_f32 v[106:107], v[130:131], v[38:39] op_sel_hi:[0,1]
	v_pk_mul_f32 v[104:105], v[130:131], v[36:37] op_sel_hi:[0,1]
	v_cvt_pk_bf16_f32 v104, v104, v105
	v_cvt_pk_bf16_f32 v105, v106, v107
	v_cvt_pk_bf16_f32 v106, v114, v115
	v_cvt_pk_bf16_f32 v107, v110, v111
	global_store_dwordx4 v[108:109], v[104:107], off
	v_pk_mul_f32 v[102:103], v[130:131], v[102:103] op_sel_hi:[0,1]
	v_pk_mul_f32 v[100:101], v[130:131], v[100:101] op_sel_hi:[0,1]
	v_pk_mul_f32 v[104:105], v[130:131], v[98:99] op_sel_hi:[0,1]
	v_pk_mul_f32 v[98:99], v[130:131], v[96:97] op_sel_hi:[0,1]
	v_cvt_pk_bf16_f32 v96, v100, v101
	v_cvt_pk_bf16_f32 v97, v102, v103
	v_cvt_pk_bf16_f32 v98, v98, v99
	v_cvt_pk_bf16_f32 v99, v104, v105
	global_store_dwordx4 v[108:109], v[96:99], off offset:256
	v_pk_mul_f32 v[102:103], v[130:131], v[26:27] op_sel_hi:[0,1]
	v_pk_mul_f32 v[104:105], v[130:131], v[24:25] op_sel_hi:[0,1]
	v_add_u32_e32 v96, 0x80, v172
	v_ashrrev_i32_e32 v99, 31, v96
	v_mad_u64_u32 v[96:97], s[0:1], s61, v96, 0
	v_mov_b32_e32 v98, v97
	v_mad_u64_u32 v[98:99], s[0:1], s61, v99, v[98:99]
	v_mov_b32_e32 v97, v98
	v_lshl_add_u64 v[96:97], v[96:97], 1, s[52:53]
	v_lshl_add_u64 v[100:101], v[96:97], 0, v[132:133]
	v_pk_mul_f32 v[98:99], v[130:131], v[30:31] op_sel_hi:[0,1]
	v_pk_mul_f32 v[96:97], v[130:131], v[28:29] op_sel_hi:[0,1]
	v_cvt_pk_bf16_f32 v96, v96, v97
	v_cvt_pk_bf16_f32 v97, v98, v99
	v_cvt_pk_bf16_f32 v98, v104, v105
	v_cvt_pk_bf16_f32 v99, v102, v103
	global_store_dwordx4 v[100:101], v[96:99], off
	v_pk_mul_f32 v[94:95], v[130:131], v[94:95] op_sel_hi:[0,1]
	v_pk_mul_f32 v[92:93], v[130:131], v[92:93] op_sel_hi:[0,1]
	v_pk_mul_f32 v[96:97], v[130:131], v[90:91] op_sel_hi:[0,1]
	v_pk_mul_f32 v[90:91], v[130:131], v[88:89] op_sel_hi:[0,1]
	v_cvt_pk_bf16_f32 v88, v92, v93
	v_cvt_pk_bf16_f32 v89, v94, v95
	v_cvt_pk_bf16_f32 v90, v90, v91
	v_cvt_pk_bf16_f32 v91, v96, v97
	global_store_dwordx4 v[100:101], v[88:91], off offset:256
	v_pk_mul_f32 v[94:95], v[130:131], v[18:19] op_sel_hi:[0,1]
	v_pk_mul_f32 v[96:97], v[130:131], v[16:17] op_sel_hi:[0,1]
	v_add_u32_e32 v88, 0x90, v172
	v_ashrrev_i32_e32 v91, 31, v88
	v_mad_u64_u32 v[88:89], s[0:1], s61, v88, 0
	v_mov_b32_e32 v90, v89
	v_mad_u64_u32 v[90:91], s[0:1], s61, v91, v[90:91]
	v_mov_b32_e32 v89, v90
	v_lshl_add_u64 v[88:89], v[88:89], 1, s[52:53]
	v_lshl_add_u64 v[92:93], v[88:89], 0, v[132:133]
	v_pk_mul_f32 v[90:91], v[130:131], v[22:23] op_sel_hi:[0,1]
	v_pk_mul_f32 v[88:89], v[130:131], v[20:21] op_sel_hi:[0,1]
	v_cvt_pk_bf16_f32 v88, v88, v89
	v_cvt_pk_bf16_f32 v89, v90, v91
	v_cvt_pk_bf16_f32 v90, v96, v97
	v_cvt_pk_bf16_f32 v91, v94, v95
	global_store_dwordx4 v[92:93], v[88:91], off
	v_pk_mul_f32 v[86:87], v[130:131], v[86:87] op_sel_hi:[0,1]
	v_pk_mul_f32 v[84:85], v[130:131], v[84:85] op_sel_hi:[0,1]
	v_pk_mul_f32 v[88:89], v[130:131], v[82:83] op_sel_hi:[0,1]
	v_pk_mul_f32 v[82:83], v[130:131], v[80:81] op_sel_hi:[0,1]
	v_cvt_pk_bf16_f32 v80, v84, v85
	v_cvt_pk_bf16_f32 v81, v86, v87
	v_cvt_pk_bf16_f32 v82, v82, v83
	v_cvt_pk_bf16_f32 v83, v88, v89
	global_store_dwordx4 v[92:93], v[80:83], off offset:256
	v_pk_mul_f32 v[86:87], v[130:131], v[10:11] op_sel_hi:[0,1]
	v_pk_mul_f32 v[88:89], v[130:131], v[8:9] op_sel_hi:[0,1]
	v_add_u32_e32 v80, 0xa0, v172
	v_ashrrev_i32_e32 v83, 31, v80
	v_mad_u64_u32 v[80:81], s[0:1], s61, v80, 0
	v_mov_b32_e32 v82, v81
	v_mad_u64_u32 v[82:83], s[0:1], s61, v83, v[82:83]
	v_mov_b32_e32 v81, v82
	v_lshl_add_u64 v[80:81], v[80:81], 1, s[52:53]
	v_lshl_add_u64 v[84:85], v[80:81], 0, v[132:133]
	v_pk_mul_f32 v[82:83], v[130:131], v[14:15] op_sel_hi:[0,1]
	v_pk_mul_f32 v[80:81], v[130:131], v[12:13] op_sel_hi:[0,1]
	v_cvt_pk_bf16_f32 v80, v80, v81
	v_cvt_pk_bf16_f32 v81, v82, v83
	v_cvt_pk_bf16_f32 v82, v88, v89
	v_cvt_pk_bf16_f32 v83, v86, v87
	global_store_dwordx4 v[84:85], v[80:83], off
	v_pk_mul_f32 v[78:79], v[130:131], v[78:79] op_sel_hi:[0,1]
	v_pk_mul_f32 v[76:77], v[130:131], v[76:77] op_sel_hi:[0,1]
	v_pk_mul_f32 v[80:81], v[130:131], v[74:75] op_sel_hi:[0,1]
	v_pk_mul_f32 v[74:75], v[130:131], v[72:73] op_sel_hi:[0,1]
	v_cvt_pk_bf16_f32 v72, v76, v77
	v_cvt_pk_bf16_f32 v73, v78, v79
	v_cvt_pk_bf16_f32 v74, v74, v75
	v_cvt_pk_bf16_f32 v75, v80, v81
	global_store_dwordx4 v[84:85], v[72:75], off offset:256
	v_pk_mul_f32 v[78:79], v[130:131], v[2:3] op_sel_hi:[0,1]
	v_pk_mul_f32 v[80:81], v[130:131], v[0:1] op_sel_hi:[0,1]
	v_add_u32_e32 v72, 0xb0, v172
	v_ashrrev_i32_e32 v75, 31, v72
	v_mad_u64_u32 v[72:73], s[0:1], s61, v72, 0
	v_mov_b32_e32 v74, v73
	v_mad_u64_u32 v[74:75], s[0:1], s61, v75, v[74:75]
	v_mov_b32_e32 v73, v74
	v_lshl_add_u64 v[72:73], v[72:73], 1, s[52:53]
	v_lshl_add_u64 v[76:77], v[72:73], 0, v[132:133]
	v_pk_mul_f32 v[74:75], v[130:131], v[6:7] op_sel_hi:[0,1]
	v_pk_mul_f32 v[72:73], v[130:131], v[4:5] op_sel_hi:[0,1]
	v_cvt_pk_bf16_f32 v72, v72, v73
	v_cvt_pk_bf16_f32 v73, v74, v75
	v_cvt_pk_bf16_f32 v74, v80, v81
	v_cvt_pk_bf16_f32 v75, v78, v79
	global_store_dwordx4 v[76:77], v[72:75], off
	v_pk_mul_f32 v[66:67], v[130:131], v[66:67] op_sel_hi:[0,1]
	v_pk_mul_f32 v[64:65], v[130:131], v[64:65] op_sel_hi:[0,1]
	v_pk_mul_f32 v[72:73], v[130:131], v[62:63] op_sel_hi:[0,1]
	v_pk_mul_f32 v[62:63], v[130:131], v[60:61] op_sel_hi:[0,1]
	v_cvt_pk_bf16_f32 v60, v64, v65
	v_cvt_pk_bf16_f32 v61, v66, v67
	v_cvt_pk_bf16_f32 v62, v62, v63
	v_cvt_pk_bf16_f32 v63, v72, v73
	global_store_dwordx4 v[76:77], v[60:63], off offset:256
	s_mov_b64 s[0:1], 0
	s_mov_b32 s32, 1
